# mixer C per-unit bias table fill: the two serialized copy loops replaced by straight-line code (up to 4 predicated loads in flight, one wait, 4 predicated LDS writes)
# speedup vs baseline: 1.0022x; 1.0010x over previous
.LBB0_2666:
	s_lshl_b32 s1, s39, 7
	s_and_b32 s1, s1, 0x300
	s_ashr_i32 s10, s39, 7
	s_bfe_u32 s42, s39, 0x40003
	s_and_b32 s0, s39, 1
	s_xor_b32 s6, s1, 0x700
	s_cmp_eq_u32 s0, 0
	s_cselect_b32 s43, s6, s1
	s_ashr_i32 s11, s10, 31
	s_add_i32 s0, s43, 0x100
	s_lshl_b64 s[12:13], s[10:11], 22
	s_lshl_b32 s33, s42, 7
	s_lshl_b64 s[6:7], s[10:11], 23
	s_add_u32 s1, s28, s6
	v_readfirstlane_b32 s15, v0
	s_addc_u32 s14, s29, s7
	s_cmpk_gt_u32 s15, 0xff
	s_mov_b64 s[6:7], -1
	s_cbranch_scc0 .LBB0_2702
	v_mov_b32_e32 v4, v0
	s_movk_i32 s6, 0x78
	v_readfirstlane_b32 s46, v4
	s_ashr_i32 s40, s46, 6
	s_lshl_b32 s16, s40, 3
	v_bfe_u32 v2, v4, 4, 2
	v_or_b32_e32 v5, s16, v2
	v_bitop3_b32 v2, s16, v4, v2 bitop3:0x36
	v_lshlrev_b32_e32 v6, 11, v5
	v_lshlrev_b32_e32 v2, 3, v2
	v_and_or_b32 v178, v2, s6, v6
	v_or_b32_e32 v2, 4, v5
	v_bitop3_b32 v5, v5, v4, 4 bitop3:0x36
	s_lshl_b32 s44, s40, 5
	v_lshlrev_b32_e32 v2, 11, v2
	v_lshlrev_b32_e32 v5, 3, v5
	s_add_i32 s15, s44, s43
	v_and_or_b32 v180, v5, s6, v2
	s_lshl_b64 s[6:7], s[12:13], 1
	s_add_u32 s6, s4, s6
	s_addc_u32 s7, s5, s7
	s_lshl_b32 s74, s33, 1
	s_add_u32 s18, s6, s74
	s_addc_u32 s19, s7, 0
	v_bfe_u32 v2, v4, 2, 3
	v_lshrrev_b32_e32 v5, 1, v4
	s_lshl_b32 s6, s40, 2
	v_bitop3_b32 v2, s16, v222, v2 bitop3:0xc8
	v_and_b32_e32 v5, 8, v5
	s_and_b32 s6, s6, 4
	v_or3_b32 v2, v5, v2, s6
	s_lshl_b32 s6, s40, 11
	v_ashrrev_i32_e32 v179, 31, v178
	v_lshlrev_b32_e32 v6, 3, v4
	s_add_i32 s45, s6, 0
	v_lshlrev_b64 v[10:11], 1, v[178:179]
	v_lshlrev_b32_e32 v2, 11, v2
	v_and_b32_e32 v5, 32, v4
	v_and_b32_e32 v6, 24, v6
	v_lshl_add_u64 v[12:13], s[18:19], 0, v[10:11]
	s_mov_b32 m0, s45
	v_or3_b32 v6, v2, v5, v6
	s_lshl_b64 s[16:17], s[10:11], 11
	global_load_lds_dwordx4 v[12:13], off
	v_ashrrev_i32_e32 v181, 31, v180
	s_add_i32 m0, s45, 0x400
	v_lshlrev_b64 v[12:13], 1, v[180:181]
	s_add_u32 s6, s1, s74
	v_ashrrev_i32_e32 v7, 31, v6
	v_or_b32_e32 v8, 64, v6
	v_lshl_add_u64 v[14:15], s[18:19], 0, v[12:13]
	s_addc_u32 s7, s14, 0
	v_lshlrev_b64 v[6:7], 1, v[6:7]
	global_load_lds_dwordx4 v[14:15], off
	s_add_i32 m0, s45, 0xc000
	v_lshl_add_u64 v[182:183], s[6:7], 0, v[6:7]
	global_load_lds_dwordx4 v[182:183], off
	s_add_i32 m0, s45, 0xc400
	s_add_u32 s20, s18, 0x40000
	v_lshl_add_u64 v[14:15], v[182:183], 0, s[94:95]
	s_addc_u32 s21, s19, 0
	global_load_lds_dwordx4 v[14:15], off
	s_add_i32 m0, s45, 0x4000
	v_lshl_add_u64 v[16:17], s[20:21], 0, v[10:11]
	global_load_lds_dwordx4 v[16:17], off
	s_add_i32 m0, s45, 0x4400
	s_add_u32 s6, s6, 0x40000
	v_lshl_add_u64 v[16:17], s[20:21], 0, v[12:13]
	s_addc_u32 s7, s7, 0
	global_load_lds_dwordx4 v[16:17], off
	s_add_i32 m0, s45, 0x10000
	v_lshl_add_u64 v[6:7], s[6:7], 0, v[6:7]
	v_ashrrev_i32_e32 v9, 31, v8
	global_load_lds_dwordx4 v[6:7], off
	s_add_i32 m0, s45, 0x10400
	v_lshl_add_u64 v[6:7], v[8:9], 1, s[6:7]
	s_add_u32 s6, s18, 0x80000
	v_and_b32_e32 v186, 31, v4
	s_addc_u32 s7, s19, 0
	v_or_b32_e32 v14, s15, v186
	global_load_lds_dwordx4 v[6:7], off
	s_add_i32 m0, s45, 0x8000
	v_lshl_add_u64 v[6:7], s[6:7], 0, v[10:11]
	global_load_lds_dwordx4 v[6:7], off
	v_lshl_add_u64 v[6:7], s[6:7], 0, v[12:13]
	s_add_i32 m0, s45, 0x8400
	v_ashrrev_i32_e32 v15, 31, v14
	global_load_lds_dwordx4 v[6:7], off
	v_lshl_add_u64 v[6:7], s[16:17], 0, v[14:15]
	v_lshlrev_b64 v[6:7], 12, v[6:7]
	v_bfe_u32 v187, v4, 5, 1
	v_lshl_add_u64 v[6:7], s[8:9], 0, v[6:7]
	v_lshl_add_u64 v[6:7], v[6:7], 0, s[74:75]
	v_lshlrev_b32_e32 v184, 4, v187
	v_mov_b32_e32 v185, v3
	v_lshl_add_u64 v[6:7], v[6:7], 0, v[184:185]
	global_load_dwordx4 v[146:149], v[6:7], off
	global_load_dwordx4 v[150:153], v[6:7], off offset:32
	global_load_dwordx4 v[154:157], v[6:7], off offset:64
	global_load_dwordx4 v[158:161], v[6:7], off offset:96
	global_load_dwordx4 v[162:165], v[6:7], off offset:128
	global_load_dwordx4 v[166:169], v[6:7], off offset:160
	global_load_dwordx4 v[170:173], v[6:7], off offset:192
	global_load_dwordx4 v[174:177], v[6:7], off offset:224
	v_cmp_gt_i32_e32 vcc, s0, v4
	s_and_saveexec_b64 s[6:7], vcc
	s_cbranch_execz .LBB0_2675
	s_lshl_b64 s[24:25], s[10:11], 17
	s_lshl_b32 s47, s42, 13
	s_add_u32 s24, s24, s36
	s_addc_u32 s25, s25, s37
	s_add_u32 s24, s24, s47
	s_addc_u32 s25, s25, 0
	v_readlane_b32 s47, v254, 50
	v_lshlrev_b32_e32 v6, 2, v4
	s_mov_b64 s[26:27], exec
	global_load_dword v5, v6, s[24:25]
	v_add_u32_e32 v7, 0x200, v4
	v_lshl_add_u32 v2, v4, 2, s47
	v_cmp_gt_i32_e32 vcc, s0, v7
	s_nop 1
	s_and_b64 s[20:21], s[26:27], vcc
	s_mov_b64 exec, s[20:21]
	global_load_dword v8, v6, s[24:25] offset:2048
	v_add_u32_e32 v7, 0x400, v4
	v_cmp_gt_i32_e32 vcc, s0, v7
	s_nop 1
	s_and_b64 s[22:23], s[20:21], vcc
	s_mov_b64 exec, s[22:23]
	v_add_u32_e32 v9, 0x1000, v6
	global_load_dword v10, v9, s[24:25]
	v_add_u32_e32 v7, 0x600, v4
	v_cmp_gt_i32_e32 vcc, s0, v7
	s_nop 1
	s_and_b64 s[98:99], s[22:23], vcc
	s_mov_b64 exec, s[98:99]
	global_load_dword v11, v9, s[24:25] offset:2048
	s_waitcnt vmcnt(0)
	ds_write_b32 v2, v11 offset:6144
	s_mov_b64 exec, s[22:23]
	ds_write_b32 v2, v10 offset:4096
	s_mov_b64 exec, s[20:21]
	ds_write_b32 v2, v8 offset:2048
	s_mov_b64 exec, s[26:27]
	ds_write_b32 v2, v5

.LBB0_2702:
	s_and_b64 vcc, exec, s[6:7]
	s_cbranch_vccz .LBB0_2665
	v_mov_b32_e32 v4, v0
	s_movk_i32 s6, 0x78
	v_readfirstlane_b32 s27, v4
	s_ashr_i32 s24, s27, 6
	s_lshl_b32 s18, s24, 3
	v_bfe_u32 v2, v4, 4, 2
	v_or_b32_e32 v5, s18, v2
	v_bitop3_b32 v2, s18, v4, v2 bitop3:0x36
	v_lshlrev_b32_e32 v6, 11, v5
	v_lshlrev_b32_e32 v2, 3, v2
	v_and_or_b32 v178, v2, s6, v6
	v_or_b32_e32 v2, 4, v5
	v_bitop3_b32 v5, v5, v4, 4 bitop3:0x36
	s_lshl_b32 s25, s24, 5
	v_lshlrev_b32_e32 v2, 11, v2
	v_lshlrev_b32_e32 v5, 3, v5
	s_add_i32 s15, s25, s43
	v_and_or_b32 v180, v5, s6, v2
	s_lshl_b64 s[6:7], s[12:13], 1
	s_add_u32 s6, s4, s6
	s_addc_u32 s7, s5, s7
	s_lshl_b32 s74, s33, 1
	s_add_u32 s16, s6, s74
	s_addc_u32 s17, s7, 0
	v_bfe_u32 v2, v4, 2, 3
	v_lshrrev_b32_e32 v5, 1, v4
	s_lshl_b32 s6, s24, 2
	v_bitop3_b32 v2, s18, v222, v2 bitop3:0xc8
	v_and_b32_e32 v5, 8, v5
	s_and_b32 s6, s6, 4
	v_or3_b32 v2, v5, v2, s6
	s_lshl_b32 s6, s24, 11
	v_ashrrev_i32_e32 v179, 31, v178
	v_lshlrev_b32_e32 v6, 3, v4
	s_add_i32 s26, s6, 0
	v_lshlrev_b64 v[10:11], 1, v[178:179]
	v_lshlrev_b32_e32 v2, 11, v2
	v_and_b32_e32 v5, 32, v4
	v_and_b32_e32 v6, 24, v6
	v_lshl_add_u64 v[12:13], s[16:17], 0, v[10:11]
	s_mov_b32 m0, s26
	v_or3_b32 v6, v2, v5, v6
	s_lshl_b64 s[12:13], s[10:11], 11
	global_load_lds_dwordx4 v[12:13], off
	v_ashrrev_i32_e32 v181, 31, v180
	s_add_i32 m0, s26, 0x400
	v_lshlrev_b64 v[12:13], 1, v[180:181]
	s_add_u32 s6, s1, s74
	v_ashrrev_i32_e32 v7, 31, v6
	v_or_b32_e32 v8, 64, v6
	v_lshl_add_u64 v[14:15], s[16:17], 0, v[12:13]
	s_addc_u32 s7, s14, 0
	v_lshlrev_b64 v[6:7], 1, v[6:7]
	global_load_lds_dwordx4 v[14:15], off
	s_add_i32 m0, s26, 0xc000
	v_lshl_add_u64 v[182:183], s[6:7], 0, v[6:7]
	global_load_lds_dwordx4 v[182:183], off
	s_add_i32 m0, s26, 0xc400
	s_add_u32 s18, s16, 0x40000
	v_lshl_add_u64 v[14:15], v[182:183], 0, s[94:95]
	s_addc_u32 s19, s17, 0
	global_load_lds_dwordx4 v[14:15], off
	s_add_i32 m0, s26, 0x4000
	v_lshl_add_u64 v[16:17], s[18:19], 0, v[10:11]
	global_load_lds_dwordx4 v[16:17], off
	s_add_i32 m0, s26, 0x4400
	s_add_u32 s6, s6, 0x40000
	v_lshl_add_u64 v[16:17], s[18:19], 0, v[12:13]
	s_addc_u32 s7, s7, 0
	global_load_lds_dwordx4 v[16:17], off
	s_add_i32 m0, s26, 0x10000
	v_lshl_add_u64 v[6:7], s[6:7], 0, v[6:7]
	v_ashrrev_i32_e32 v9, 31, v8
	global_load_lds_dwordx4 v[6:7], off
	s_add_i32 m0, s26, 0x10400
	v_lshl_add_u64 v[6:7], v[8:9], 1, s[6:7]
	s_add_u32 s6, s16, 0x80000
	v_and_b32_e32 v186, 31, v4
	s_addc_u32 s7, s17, 0
	v_or_b32_e32 v14, s15, v186
	global_load_lds_dwordx4 v[6:7], off
	s_add_i32 m0, s26, 0x8000
	v_lshl_add_u64 v[6:7], s[6:7], 0, v[10:11]
	global_load_lds_dwordx4 v[6:7], off
	v_lshl_add_u64 v[6:7], s[6:7], 0, v[12:13]
	s_add_i32 m0, s26, 0x8400
	v_ashrrev_i32_e32 v15, 31, v14
	global_load_lds_dwordx4 v[6:7], off
	v_lshl_add_u64 v[6:7], s[12:13], 0, v[14:15]
	v_lshlrev_b64 v[6:7], 12, v[6:7]
	v_bfe_u32 v187, v4, 5, 1
	v_lshl_add_u64 v[6:7], s[8:9], 0, v[6:7]
	v_lshl_add_u64 v[6:7], v[6:7], 0, s[74:75]
	v_lshlrev_b32_e32 v184, 4, v187
	v_mov_b32_e32 v185, v3
	v_lshl_add_u64 v[6:7], v[6:7], 0, v[184:185]
	global_load_dwordx4 v[146:149], v[6:7], off
	global_load_dwordx4 v[150:153], v[6:7], off offset:32
	global_load_dwordx4 v[154:157], v[6:7], off offset:64
	global_load_dwordx4 v[158:161], v[6:7], off offset:96
	global_load_dwordx4 v[162:165], v[6:7], off offset:128
	global_load_dwordx4 v[166:169], v[6:7], off offset:160
	global_load_dwordx4 v[170:173], v[6:7], off offset:192
	global_load_dwordx4 v[174:177], v[6:7], off offset:224
	v_cmp_gt_i32_e32 vcc, s0, v4
	s_and_saveexec_b64 s[6:7], vcc
	s_cbranch_execz .LBB0_2711
	s_lshl_b64 s[20:21], s[10:11], 17
	s_lshl_b32 s1, s42, 13
	s_add_u32 s20, s20, s36
	s_addc_u32 s21, s21, s37
	s_add_u32 s20, s20, s1
	s_addc_u32 s21, s21, 0
	v_readlane_b32 s1, v254, 50
	v_lshlrev_b32_e32 v6, 2, v4
	s_mov_b64 s[22:23], exec
	global_load_dword v5, v6, s[20:21]
	v_add_u32_e32 v7, 0x200, v4
	v_lshl_add_u32 v2, v4, 2, s1
	v_cmp_gt_i32_e32 vcc, s0, v7
	s_nop 1
	s_and_b64 s[18:19], s[22:23], vcc
	s_mov_b64 exec, s[18:19]
	global_load_dword v8, v6, s[20:21] offset:2048
	v_add_u32_e32 v7, 0x400, v4
	v_cmp_gt_i32_e32 vcc, s0, v7
	s_nop 1
	s_and_b64 s[10:11], s[18:19], vcc
	s_mov_b64 exec, s[10:11]
	v_add_u32_e32 v9, 0x1000, v6
	global_load_dword v10, v9, s[20:21]
	v_add_u32_e32 v7, 0x600, v4
	v_cmp_gt_i32_e32 vcc, s0, v7
	s_nop 1
	s_and_b64 s[98:99], s[10:11], vcc
	s_mov_b64 exec, s[98:99]
	global_load_dword v11, v9, s[20:21] offset:2048
	s_waitcnt vmcnt(0)
	ds_write_b32 v2, v11 offset:6144
	s_mov_b64 exec, s[10:11]
	ds_write_b32 v2, v10 offset:4096
	s_mov_b64 exec, s[18:19]
	ds_write_b32 v2, v8 offset:2048
	s_mov_b64 exec, s[22:23]
	ds_write_b32 v2, v5
